# FoX: pre-softmax barrier executed 4 MFMAs before the end of the MFMA half (all LDS reads landed) so the partner group starts under the last MFMAs
# speedup vs baseline: 1.0058x; 1.0058x over previous
.Lfx_dm5_pq:
	s_waitcnt lgkmcnt(4)
	v_mfma_f32_32x32x16_bf16 v[16:31], v[228:231], v[200:203], v[16:31]
	v_add_u32_e32 v15, v14, v176
	ds_read_b128 v[212:215], v15
	s_waitcnt lgkmcnt(3)
	v_mfma_f32_32x32x16_bf16 v[16:31], v[232:235], v[208:211], v[16:31]
	ds_read_b128 v[216:219], v15 offset:8192
	s_waitcnt lgkmcnt(3)
	v_mfma_f32_32x32x16_bf16 v[96:111], v[2:5], v[112:115], v[96:111]
	v_add_u32_e32 v15, v14, v177
	ds_read_b128 v[220:223], v15
	s_waitcnt lgkmcnt(3)
	v_mfma_f32_32x32x16_bf16 v[80:95], v[6:9], v[112:115], v[80:95]
	ds_read_b128 v[224:227], v15 offset:8192
	s_waitcnt lgkmcnt(3)
	v_mfma_f32_32x32x16_bf16 v[96:111], v[212:215], v[116:119], v[96:111]
	v_add_u32_e32 v15, v14, v178
	ds_read_b128 v[228:231], v15
	s_waitcnt lgkmcnt(3)
	v_mfma_f32_32x32x16_bf16 v[80:95], v[216:219], v[116:119], v[80:95]
	ds_read_b128 v[232:235], v15 offset:8192
	s_waitcnt lgkmcnt(3)
	v_mfma_f32_32x32x16_bf16 v[96:111], v[220:223], v[120:123], v[96:111]
	v_add_u32_e32 v15, v14, v179
	ds_read_b128 v[2:5], v15
	s_waitcnt lgkmcnt(3)
	v_mfma_f32_32x32x16_bf16 v[80:95], v[224:227], v[120:123], v[80:95]
	ds_read_b128 v[6:9], v15 offset:8192
	s_waitcnt lgkmcnt(3)
	v_mfma_f32_32x32x16_bf16 v[96:111], v[228:231], v[124:127], v[96:111]
	v_add_u32_e32 v15, v14, v180
	ds_read_b128 v[212:215], v15
	s_waitcnt lgkmcnt(3)
	v_mfma_f32_32x32x16_bf16 v[80:95], v[232:235], v[124:127], v[80:95]
	ds_read_b128 v[216:219], v15 offset:8192
	s_waitcnt lgkmcnt(3)
	v_mfma_f32_32x32x16_bf16 v[96:111], v[2:5], v[128:131], v[96:111]
	v_add_u32_e32 v15, v14, v181
	ds_read_b128 v[220:223], v15
	s_waitcnt lgkmcnt(3)
	v_mfma_f32_32x32x16_bf16 v[80:95], v[6:9], v[128:131], v[80:95]
	ds_read_b128 v[224:227], v15 offset:8192
	s_waitcnt lgkmcnt(3)
	v_mfma_f32_32x32x16_bf16 v[96:111], v[212:215], v[132:135], v[96:111]
	v_add_u32_e32 v15, v14, v182
	ds_read_b128 v[228:231], v15
	s_waitcnt lgkmcnt(3)
	v_mfma_f32_32x32x16_bf16 v[80:95], v[216:219], v[132:135], v[80:95]
	ds_read_b128 v[232:235], v15 offset:8192
	s_waitcnt lgkmcnt(0)
	s_cmp_eq_u32 s84, 0
	s_cbranch_scc1 .Lfx_hw0_pq
	s_waitcnt vmcnt(4)
	s_branch .Lfx_hw1_pq

.Lfx_hw1_pq:
	s_barrier
	v_mfma_f32_32x32x16_bf16 v[96:111], v[220:223], v[136:139], v[96:111]
	v_mfma_f32_32x32x16_bf16 v[80:95], v[224:227], v[136:139], v[80:95]
	v_mfma_f32_32x32x16_bf16 v[96:111], v[228:231], v[140:143], v[96:111]
	v_mfma_f32_32x32x16_bf16 v[80:95], v[232:235], v[140:143], v[80:95]
	s_nop 7
	s_branch .Lfx_h1_joined

.Lfx_dm6_q:
	s_waitcnt lgkmcnt(3)
	v_mfma_f32_32x32x16_bf16 v[96:111], v[212:215], v[116:119], v[96:111]
	v_add_u32_e32 v15, v14, v178
	ds_read_b128 v[228:231], v15
	s_waitcnt lgkmcnt(3)
	v_mfma_f32_32x32x16_bf16 v[80:95], v[216:219], v[116:119], v[80:95]
	ds_read_b128 v[232:235], v15 offset:8192
	s_cmp_eq_u32 s84, 0
	s_cbranch_scc1 .Lfx_dm7_q
	s_add_i32 m0, s33, 0x400
	s_nop 0
	global_load_lds_dwordx4 v189, s[28:29]
.Lfx_dm7_q:
	s_waitcnt lgkmcnt(3)
	v_mfma_f32_32x32x16_bf16 v[96:111], v[220:223], v[120:123], v[96:111]
	v_add_u32_e32 v15, v14, v179
	ds_read_b128 v[2:5], v15
	s_waitcnt lgkmcnt(3)
	v_mfma_f32_32x32x16_bf16 v[80:95], v[224:227], v[120:123], v[80:95]
	ds_read_b128 v[6:9], v15 offset:8192
	s_cmp_eq_u32 s84, 0
	s_cbranch_scc1 .Lfx_dm8_q
	s_add_i32 m0, s33, 0x800
	s_nop 0
	global_load_lds_dwordx4 v190, s[28:29]
.Lfx_dm8_q:
	s_waitcnt lgkmcnt(3)
	v_mfma_f32_32x32x16_bf16 v[96:111], v[228:231], v[124:127], v[96:111]
	v_add_u32_e32 v15, v14, v180
	ds_read_b128 v[212:215], v15
	s_waitcnt lgkmcnt(3)
	v_mfma_f32_32x32x16_bf16 v[80:95], v[232:235], v[124:127], v[80:95]
	ds_read_b128 v[216:219], v15 offset:8192
	s_cmp_eq_u32 s84, 0
	s_cbranch_scc1 .Lfx_dm9_q
	s_add_i32 m0, s33, 0xc00
	s_nop 0
	global_load_lds_dwordx4 v191, s[28:29]
.Lfx_dm9_q:
	s_waitcnt lgkmcnt(3)
	v_mfma_f32_32x32x16_bf16 v[96:111], v[2:5], v[128:131], v[96:111]
	v_add_u32_e32 v15, v14, v181
	ds_read_b128 v[220:223], v15
	s_waitcnt lgkmcnt(3)
	v_mfma_f32_32x32x16_bf16 v[80:95], v[6:9], v[128:131], v[80:95]
	ds_read_b128 v[224:227], v15 offset:8192
	s_cmp_eq_u32 s86, 0
	s_cbranch_scc1 .Lfx_dm10_q
	s_add_i32 m0, s72, s77
	s_nop 0
	global_load_lds_dword v172, s[68:69]
.Lfx_dm10_q:
	s_waitcnt lgkmcnt(3)
	v_mfma_f32_32x32x16_bf16 v[96:111], v[212:215], v[132:135], v[96:111]
	v_add_u32_e32 v15, v14, v182
	ds_read_b128 v[228:231], v15
	s_waitcnt lgkmcnt(3)
	v_mfma_f32_32x32x16_bf16 v[80:95], v[216:219], v[132:135], v[80:95]
	ds_read_b128 v[232:235], v15 offset:8192
	s_waitcnt lgkmcnt(0)
	s_cmp_eq_u32 s84, 0
	s_cbranch_scc1 .Lfx_hw0_q
	s_waitcnt vmcnt(4)
	s_branch .Lfx_hw1_q

.Lfx_hw1_q:
	s_barrier
	v_mfma_f32_32x32x16_bf16 v[96:111], v[220:223], v[136:139], v[96:111]
	v_mfma_f32_32x32x16_bf16 v[80:95], v[224:227], v[136:139], v[80:95]
	v_mfma_f32_32x32x16_bf16 v[96:111], v[228:231], v[140:143], v[96:111]
	v_mfma_f32_32x32x16_bf16 v[80:95], v[232:235], v[140:143], v[80:95]
	s_add_i32 s29, s62, 0xc0000001
	s_cmp_gt_u32 s29, 0xc000005d
	s_cbranch_scc1 .Lfx_nomask_q
	s_nop 11
	v_add_u32_e32 v0, s62, v147
	v_subrev_u32_e32 v2, 30, v0
	v_cmp_gt_u32_e32 vcc, 2.0, v2
	v_add_u32_e32 v2, 0xbfffffc2, v0
	s_nop 3
	v_cndmask_b32_e32 v96, v187, v96, vcc
	v_cmp_lt_u32_e32 vcc, s17, v2
	v_subrev_u32_e32 v2, 31, v0
	s_nop 0
	v_cndmask_b32_e32 v80, v187, v80, vcc
	v_cmp_gt_u32_e32 vcc, 2.0, v2
	v_add_u32_e32 v2, 0xbfffffc1, v0
	s_nop 0
	v_cndmask_b32_e32 v97, v187, v97, vcc
	v_cmp_lt_u32_e32 vcc, s17, v2
	v_subrev_u32_e32 v2, 32, v0
	s_nop 0
	v_cndmask_b32_e32 v81, v187, v81, vcc
	v_cmp_gt_u32_e32 vcc, 2.0, v2
	v_add_u32_e32 v2, 0xbfffffc0, v0
	s_nop 0
	v_cndmask_b32_e32 v98, v187, v98, vcc
	v_cmp_lt_u32_e32 vcc, s17, v2
	v_subrev_u32_e32 v2, 33, v0
	s_nop 0
	v_cndmask_b32_e32 v82, v187, v82, vcc
	v_cmp_gt_u32_e32 vcc, 2.0, v2
	v_add_u32_e32 v2, 0xbfffffbf, v0
	s_nop 0
	v_cndmask_b32_e32 v99, v187, v99, vcc
	v_cmp_lt_u32_e32 vcc, s17, v2
	v_subrev_u32_e32 v2, 38, v0
	s_nop 0
	v_cndmask_b32_e32 v83, v187, v83, vcc
	v_cmp_gt_u32_e32 vcc, 2.0, v2
	v_add_u32_e32 v2, 0xbfffffba, v0
	s_nop 0
	v_cndmask_b32_e32 v100, v187, v100, vcc
	v_cmp_lt_u32_e32 vcc, s17, v2
	v_subrev_u32_e32 v2, 39, v0
	s_nop 0
	v_cndmask_b32_e32 v84, v187, v84, vcc
	v_cmp_gt_u32_e32 vcc, 2.0, v2
	v_add_u32_e32 v2, 0xbfffffb9, v0
	s_nop 0
	v_cndmask_b32_e32 v101, v187, v101, vcc
	v_cmp_lt_u32_e32 vcc, s17, v2
	v_subrev_u32_e32 v2, 40, v0
	s_nop 0
	v_cndmask_b32_e32 v85, v187, v85, vcc
	v_cmp_gt_u32_e32 vcc, 2.0, v2
	v_add_u32_e32 v2, 0xbfffffb8, v0
	s_nop 0
	v_cndmask_b32_e32 v102, v187, v102, vcc
	v_cmp_lt_u32_e32 vcc, s17, v2
	v_subrev_u32_e32 v2, 41, v0
	s_nop 0
	v_cndmask_b32_e32 v86, v187, v86, vcc
	v_cmp_gt_u32_e32 vcc, 2.0, v2
	v_add_u32_e32 v2, 0xbfffffb7, v0
	s_nop 0
	v_cndmask_b32_e32 v103, v187, v103, vcc
	v_cmp_lt_u32_e32 vcc, s17, v2
	v_subrev_u32_e32 v2, 46, v0
	s_nop 0
	v_cndmask_b32_e32 v87, v187, v87, vcc
	v_cmp_gt_u32_e32 vcc, 2.0, v2
	v_add_u32_e32 v2, 0xbfffffb2, v0
	s_nop 0
	v_cndmask_b32_e32 v104, v187, v104, vcc
	v_cmp_lt_u32_e32 vcc, s17, v2
	v_subrev_u32_e32 v2, 47, v0
	s_nop 0
	v_cndmask_b32_e32 v88, v187, v88, vcc
	v_cmp_gt_u32_e32 vcc, 2.0, v2
	v_add_u32_e32 v2, 0xbfffffb1, v0
	s_nop 0
	v_cndmask_b32_e32 v105, v187, v105, vcc
	v_cmp_lt_u32_e32 vcc, s17, v2
	v_subrev_u32_e32 v2, 48, v0
	s_nop 0
	v_cndmask_b32_e32 v89, v187, v89, vcc
	v_cmp_gt_u32_e32 vcc, 2.0, v2
	v_add_u32_e32 v2, 0xbfffffb0, v0
	s_nop 0
	v_cndmask_b32_e32 v106, v187, v106, vcc
	v_cmp_lt_u32_e32 vcc, s17, v2
	v_subrev_u32_e32 v2, 49, v0
	s_nop 0
	v_cndmask_b32_e32 v90, v187, v90, vcc
	v_cmp_gt_u32_e32 vcc, 2.0, v2
	v_add_u32_e32 v2, 0xbfffffaf, v0
	s_nop 0
	v_cndmask_b32_e32 v107, v187, v107, vcc
	v_cmp_lt_u32_e32 vcc, s17, v2
	v_subrev_u32_e32 v2, 54, v0
	s_nop 0
	v_cndmask_b32_e32 v91, v187, v91, vcc
	v_cmp_gt_u32_e32 vcc, 2.0, v2
	v_add_u32_e32 v2, 0xbfffffaa, v0
	s_nop 0
	v_cndmask_b32_e32 v108, v187, v108, vcc
	v_cmp_lt_u32_e32 vcc, s17, v2
	v_subrev_u32_e32 v2, 55, v0
	s_nop 0
	v_cndmask_b32_e32 v92, v187, v92, vcc
	v_cmp_gt_u32_e32 vcc, 2.0, v2
	v_add_u32_e32 v2, 0xbfffffa9, v0
	s_nop 0
	v_cndmask_b32_e32 v109, v187, v109, vcc
	v_cmp_lt_u32_e32 vcc, s17, v2
	v_subrev_u32_e32 v2, 56, v0
	s_nop 0
	v_cndmask_b32_e32 v93, v187, v93, vcc
	v_cmp_gt_u32_e32 vcc, 2.0, v2
	v_add_u32_e32 v2, 0xbfffffa8, v0
	s_nop 0
	v_cndmask_b32_e32 v110, v187, v110, vcc
	v_cmp_lt_u32_e32 vcc, s17, v2
	v_subrev_u32_e32 v2, 57, v0
	v_add_u32_e32 v0, 0xbfffffa7, v0
	v_cndmask_b32_e32 v94, v187, v94, vcc
	v_cmp_gt_u32_e32 vcc, 2.0, v2
	s_nop 1
	v_cndmask_b32_e32 v111, v187, v111, vcc
	v_cmp_lt_u32_e32 vcc, s17, v0
	s_nop 1
	v_cndmask_b32_e32 v95, v187, v95, vcc
.Lfx_nomask_q:
	s_nop 7
	s_branch .Lfx_h1_joined
.Lfx_h1_done:
	s_barrier
.Lfx_h1_joined:
	s_andn2_b64 vcc, exec, s[78:79]
	s_cbranch_vccnz .Lfx_h2_invis
	s_cmp_lt_i32 s41, 1
	s_cbranch_scc1 .Lfx_nv_v
	s_lshl_b32 s64, s41, 7
	s_add_i32 s66, s64, 0xffffff80
	s_ashr_i32 s67, s66, 31
	s_lshl_b64 s[30:31], s[66:67], 8
	s_add_u32 s30, s23, s30
	s_addc_u32 s31, s24, s31
	s_add_i32 m0, s74, s77
	s_nop 0
	global_load_lds_dwordx4 v188, s[30:31]
